# GEMM phase prologues: the six K-tile-1 LDS-DMA stages issue with the first eight, ahead of the stagger barrier (vmcnt 2 -> 8)
# speedup vs baseline: 1.0134x; 1.0063x over previous
.LBB0_233:
	v_mov_b32_e32 v1, v0
	s_mov_b32 s12, 0xfffe0
	v_bfe_i32 v5, v1, 27, 1
	v_lshlrev_b32_e32 v4, 4, v1
	v_lshrrev_b32_e32 v5, 22, v5
	v_add_u32_e32 v5, v4, v5
	v_and_b32_e32 v5, 0xfffffc00, v5
	v_sub_u32_e32 v5, v4, v5
	v_lshrrev_b32_e32 v6, 4, v5
	v_ashrrev_i32_e32 v2, 31, v1
	v_bitop3_b32 v5, v6, v5, 32 bitop3:0x6c
	v_lshrrev_b32_e32 v2, 26, v2
	v_ashrrev_i32_e32 v7, 31, v5
	v_add_u32_e32 v2, v1, v2
	v_lshrrev_b32_e32 v7, 26, v7
	v_ashrrev_i32_e32 v2, 6, v2
	v_add_u32_e32 v7, v5, v7
	v_lshlrev_b32_e32 v6, 3, v2
	v_ashrrev_i32_e32 v8, 6, v7
	v_and_b32_e32 v7, 0xc0, v7
	v_and_b32_e32 v6, -16, v6
	v_sub_u32_e32 v5, v5, v7
	v_add_u32_e32 v6, v8, v6
	v_lshlrev_b32_e32 v9, 5, v2
	v_ashrrev_i16_sdwa v5, v232, sext(v5) dst_sel:DWORD dst_unused:UNUSED_PAD src0_sel:DWORD src1_sel:BYTE_0
	v_and_b32_e32 v10, 32, v9
	v_bfe_i32 v9, v5, 0, 16
	v_lshlrev_b32_e32 v5, 1, v6
	v_lshrrev_b32_e32 v7, 2, v6
	v_and_b32_e32 v11, 3, v8
	v_and_b32_e32 v5, 24, v5
	v_and_b32_e32 v7, 4, v7
	v_and_or_b32 v11, v6, s12, v11
	v_or3_b32 v5, v11, v7, v5
	v_add_lshl_u32 v7, v10, v9, 1
	v_add_u32_e32 v4, 0x2000, v4
	v_lshl_add_u32 v134, v5, 12, v7
	v_ashrrev_i32_e32 v5, 31, v4
	v_lshrrev_b32_e32 v5, 22, v5
	v_add_u32_e32 v5, v4, v5
	v_ashrrev_i32_e32 v10, 10, v5
	v_mul_i32_i24_e32 v5, 0x400, v10
	v_sub_u32_e32 v4, v4, v5
	v_lshrrev_b32_e32 v5, 4, v4
	v_bitop3_b32 v4, v5, v4, 32 bitop3:0x6c
	v_lshl_add_u32 v132, v6, 12, v7
	v_ashrrev_i32_e32 v6, 31, v4
	s_mul_i32 s64, s49, 0x600000
	v_lshrrev_b32_e32 v6, 26, v6
	s_lshl_b64 s[0:1], s[64:65], 1
	v_readlane_b32 s9, v253, 45
	v_lshlrev_b32_e32 v5, 3, v10
	v_add_u32_e32 v6, v4, v6
	s_add_u32 s9, s9, s0
	v_readlane_b32 s0, v253, 46
	v_and_b32_e32 v5, -16, v5
	v_ashrrev_i32_e32 v11, 6, v6
	s_addc_u32 s23, s0, s1
	v_readfirstlane_b32 s0, v1
	v_add_u32_e32 v5, v11, v5
	v_and_b32_e32 v13, 3, v11
	v_and_b32_e32 v6, 0xc0, v6
	v_and_or_b32 v13, v5, s12, v13
	s_ashr_i32 s12, s0, 6
	s_ashr_i32 s1, s0, 8
	v_sub_u32_e32 v4, v4, v6
	s_lshl_b32 s29, s12, 10
	v_readlane_b32 s16, v252, 28
	v_ashrrev_i16_sdwa v4, v232, sext(v4) dst_sel:DWORD dst_unused:UNUSED_PAD src0_sel:DWORD src1_sel:BYTE_0
	v_readlane_b32 s17, v252, 29
	s_add_u32 s88, s9, s16
	v_lshlrev_b32_e32 v7, 5, v10
	v_bfe_i32 v12, v4, 0, 16
	v_lshlrev_b32_e32 v4, 1, v5
	v_lshrrev_b32_e32 v6, 2, v5
	s_addc_u32 s89, s23, s17
	s_add_i32 s35, s29, 0
	v_and_b32_e32 v7, 32, v7
	v_and_b32_e32 v4, 24, v4
	v_and_b32_e32 v6, 4, v6
	s_add_i32 m0, s35, 0x10000
	v_or3_b32 v4, v13, v6, v4
	v_add_lshl_u32 v6, v7, v12, 1
	global_load_lds_dwordx4 v134, s[88:89]
	s_add_i32 m0, s35, 0x12000
	v_lshl_add_u32 v138, v4, 12, v6
	s_add_u32 s16, s88, 0x80000
	global_load_lds_dwordx4 v138, s[88:89]
	s_addc_u32 s17, s89, 0
	s_add_i32 m0, s35, 0x14000
	s_add_i32 s60, s35, 0x2000
	global_load_lds_dwordx4 v134, s[16:17]
	s_add_i32 m0, s35, 0x16000
	v_lshl_add_u32 v136, v5, 12, v6
	global_load_lds_dwordx4 v138, s[16:17]
	s_mov_b32 m0, s35
	s_add_i32 s61, s35, 0x4000
	global_load_lds_dwordx4 v132, s[56:57]
	s_mov_b32 m0, s60
	v_readlane_b32 s16, v252, 30
	global_load_lds_dwordx4 v136, s[56:57]
	s_mov_b32 m0, s61
	v_readlane_b32 s17, v252, 31
	s_add_i32 s62, s35, 0x6000
	s_cmp_eq_u32 s1, 1
	v_mov_b32_e32 v135, v3
	v_mov_b32_e32 v139, v3
	s_cselect_b64 s[36:37], -1, 0
	global_load_lds_dwordx4 v132, s[16:17]
	s_mov_b32 m0, s62
	s_mov_b32 s25, s24
	global_load_lds_dwordx4 v136, s[16:17]
	s_add_u32 s98, s88, 0x80
	s_addc_u32 s99, s89, 0
	s_add_i32 m0, s35, 0x18000
	s_nop 0
	global_load_lds_dwordx4 v134, s[98:99]
	s_add_i32 m0, s35, 0x1a000
	s_nop 0
	global_load_lds_dwordx4 v138, s[98:99]
	s_add_u32 s98, s56, 0x80
	s_addc_u32 s99, s57, 0
	s_add_i32 m0, s35, 0x8000
	s_nop 0
	global_load_lds_dwordx4 v132, s[98:99]
	s_add_i32 m0, s35, 0xa000
	s_nop 0
	global_load_lds_dwordx4 v136, s[98:99]
	s_add_u32 s98, s88, 0x80080
	s_addc_u32 s99, s89, 0
	s_add_i32 m0, s35, 0x1c000
	s_nop 0
	global_load_lds_dwordx4 v134, s[98:99]
	s_add_i32 m0, s35, 0x1e000
	s_nop 0
	global_load_lds_dwordx4 v138, s[98:99]
	s_movk_i32 s24, 0xff
	v_lshl_add_u64 v[6:7], s[88:89], 0, v[134:135]
	v_lshl_add_u64 v[4:5], s[88:89], 0, v[138:139]
	s_and_b64 vcc, exec, s[36:37]
	s_cbranch_vccz .LBB0_235
	s_barrier
.LBB0_235:
	s_lshl_b32 s12, s12, 5
	v_mov_b32_e32 v133, v3
	s_and_b32 s17, s12, 0x60
	s_add_i32 m0, s35, 0x18000
	v_lshl_add_u64 v[6:7], v[6:7], 0, s[66:67]
	v_lshl_add_u64 v[14:15], s[56:57], 0, v[132:133]
	v_mov_b32_e32 v137, v3
	s_lshl_b32 s16, s1, 13
	s_lshl_b32 s33, s17, 7
	s_waitcnt vmcnt(8)
	s_barrier
	v_lshl_add_u64 v[4:5], v[4:5], 0, s[66:67]
	s_add_i32 m0, s35, 0x1a000
	s_add_i32 s63, s35, 0x8000
	s_add_i32 s64, s35, 0xa000
	v_lshl_add_u64 v[16:17], s[56:57], 0, v[136:137]
	v_lshl_add_u64 v[4:5], v[14:15], 0, s[66:67]
	s_mov_b32 m0, s63
	s_add_u32 s12, s88, 0x80080
	v_lshl_add_u64 v[4:5], v[16:17], 0, s[66:67]
	s_mov_b32 m0, s64
	s_addc_u32 s13, s89, 0
	s_add_i32 m0, s35, 0x1c000
	v_lshl_add_u64 v[4:5], s[12:13], 0, v[134:135]
	v_lshl_add_u64 v[4:5], s[12:13], 0, v[138:139]
	s_add_i32 m0, s35, 0x1e000
	s_cmpk_lt_u32 s0, 0x100
	v_lshrrev_b32_e32 v5, 1, v1
	v_and_b32_e32 v5, 24, v5
	v_and_b32_e32 v4, 15, v1
	v_lshlrev_b32_e32 v6, 1, v5
	v_lshlrev_b32_e32 v1, 2, v1
	v_bfe_u32 v140, v0, 2, 4
	v_lshl_or_b32 v140, s1, 6, v140
	v_bfe_u32 v231, v0, 2, 4
	v_and_b32_e32 v230, 3, v0
	v_lshl_or_b32 v231, v230, 4, v231
	v_lshlrev_b32_e32 v231, 2, v231
	v_lshl_or_b32 v4, v4, 6, v6
	v_and_b32_e32 v1, 32, v1
	v_bitop3_b32 v6, v4, s16, v1 bitop3:0xde
	v_bitop3_b32 v1, v4, s33, v1 bitop3:0xde
	v_lshlrev_b32_e32 v4, 15, v2
	v_and_b32_e32 v4, 0xffff0000, v4
	v_lshl_add_u32 v4, v8, 12, v4
	v_and_b32_e32 v2, 1, v2
	v_lshl_or_b32 v2, v2, 6, v4
	v_lshl_add_u32 v146, v9, 1, v2
	v_lshlrev_b32_e32 v2, 15, v10
	v_readlane_b32 s0, v252, 26
	v_and_b32_e32 v2, 0xffff0000, v2
	v_readlane_b32 s1, v252, 27
	s_waitcnt vmcnt(6)
	v_lshl_add_u32 v2, v11, 12, v2
	v_and_b32_e32 v4, 1, v10
	s_mov_b32 s50, s0
	v_readlane_b32 s0, v252, 24
	v_ashrrev_i32_e32 v141, 31, v140
	v_lshl_or_b32 v2, v4, 6, v2
	v_readlane_b32 s1, v252, 25
	s_mov_b32 s55, 32
	s_cselect_b64 s[58:59], -1, 0
	v_and_b32_e32 v142, 3, v0
	v_lshl_or_b32 v142, v142, 3, s17
	v_lshlrev_b64 v[144:145], 10, v[140:141]
	v_mov_b32_e32 v147, v3
	v_lshl_add_u32 v148, v12, 1, v2
	v_mov_b32_e32 v149, v3
	s_mov_b32 s51, 0
	v_add_u32_e32 v141, 0, v6
	s_mov_b32 s54, s0
	s_mov_b64 s[0:1], s[56:57]
	s_mov_b32 s13, 0
	s_barrier
	s_branch .LBB0_238

.LBB0_511:
	s_or_b64 exec, exec, s[0:1]
	v_mov_b32_e32 v14, v0
	s_waitcnt lgkmcnt(0)
	s_barrier
	s_mov_b32 s16, 0xfffe0
	v_ashrrev_i32_e32 v2, 31, v14
	v_lshrrev_b32_e32 v2, 26, v2
	v_add_u32_e32 v2, v14, v2
	v_ashrrev_i32_e32 v8, 6, v2
	v_bfe_i32 v2, v14, 27, 1
	v_lshlrev_b32_e32 v1, 4, v14
	v_lshrrev_b32_e32 v2, 22, v2
	v_add_u32_e32 v2, v1, v2
	v_and_b32_e32 v2, 0xfffffc00, v2
	v_sub_u32_e32 v2, v1, v2
	v_lshrrev_b32_e32 v4, 4, v2
	v_bitop3_b32 v2, v4, v2, 32 bitop3:0x6c
	v_ashrrev_i32_e32 v5, 31, v2
	v_lshrrev_b32_e32 v5, 26, v5
	v_add_u32_e32 v5, v2, v5
	v_lshlrev_b32_e32 v4, 3, v8
	v_ashrrev_i32_e32 v9, 6, v5
	v_and_b32_e32 v5, 0xc0, v5
	v_and_b32_e32 v4, -16, v4
	v_sub_u32_e32 v2, v2, v5
	v_add_u32_e32 v4, v9, v4
	v_ashrrev_i16_sdwa v2, v232, sext(v2) dst_sel:DWORD dst_unused:UNUSED_PAD src0_sel:DWORD src1_sel:BYTE_0
	v_lshlrev_b32_e32 v6, 5, v8
	v_bfe_i32 v10, v2, 0, 16
	v_lshlrev_b32_e32 v2, 1, v4
	v_lshrrev_b32_e32 v5, 2, v4
	v_and_b32_e32 v7, 3, v9
	v_and_b32_e32 v6, 32, v6
	v_and_b32_e32 v2, 24, v2
	v_and_b32_e32 v5, 4, v5
	v_and_or_b32 v7, v4, s16, v7
	v_or3_b32 v2, v7, v5, v2
	v_add_lshl_u32 v5, v6, v10, 1
	v_add_u32_e32 v1, 0x2000, v1
	v_lshl_add_u32 v132, v4, 12, v5
	v_ashrrev_i32_e32 v4, 31, v1
	v_lshrrev_b32_e32 v4, 22, v4
	v_add_u32_e32 v4, v1, v4
	v_ashrrev_i32_e32 v11, 10, v4
	v_mul_i32_i24_e32 v4, 0x400, v11
	v_sub_u32_e32 v1, v1, v4
	v_lshrrev_b32_e32 v4, 4, v1
	s_lshl_b32 s0, s49, 23
	v_readlane_b32 s1, v253, 43
	v_bitop3_b32 v1, v4, v1, 32 bitop3:0x6c
	s_add_u32 s12, s1, s0
	v_readlane_b32 s0, v253, 44
	v_lshl_add_u32 v2, v2, 12, v5
	v_ashrrev_i32_e32 v5, 31, v1
	s_addc_u32 s13, s0, 0
	v_readlane_b32 s0, v252, 7
	v_lshrrev_b32_e32 v5, 26, v5
	s_add_u32 s84, s12, s0
	v_add_u32_e32 v5, v1, v5
	s_addc_u32 s85, s13, 0
	v_lshlrev_b32_e32 v4, 3, v11
	v_ashrrev_i32_e32 v12, 6, v5
	v_and_b32_e32 v5, 0xc0, v5
	s_add_u32 s0, s84, 0x80000
	v_readfirstlane_b32 s9, v14
	v_and_b32_e32 v4, -16, v4
	v_sub_u32_e32 v1, v1, v5
	s_addc_u32 s1, s85, 0
	v_add_u32_e32 v4, v12, v4
	v_ashrrev_i16_sdwa v1, v232, sext(v1) dst_sel:DWORD dst_unused:UNUSED_PAD src0_sel:DWORD src1_sel:BYTE_0
	v_and_b32_e32 v7, 3, v12
	s_ashr_i32 s23, s9, 6
	v_lshlrev_b32_e32 v6, 5, v11
	v_bfe_i32 v13, v1, 0, 16
	v_lshlrev_b32_e32 v1, 1, v4
	v_lshrrev_b32_e32 v5, 2, v4
	v_and_or_b32 v7, v4, s16, v7
	s_lshl_b32 s16, s23, 10
	v_and_b32_e32 v6, 32, v6
	v_and_b32_e32 v1, 24, v1
	v_and_b32_e32 v5, 4, v5
	s_add_i32 s17, s16, 0
	v_or3_b32 v1, v7, v5, v1
	v_add_lshl_u32 v5, v6, v13, 1
	s_add_i32 m0, s17, 0x10000
	v_lshl_add_u32 v136, v1, 12, v5
	global_load_lds_dwordx4 v2, s[84:85]
	s_add_i32 m0, s17, 0x12000
	s_add_i32 s29, s17, 0x2000
	global_load_lds_dwordx4 v136, s[84:85]
	s_add_i32 m0, s17, 0x14000
	v_lshl_add_u32 v134, v4, 12, v5
	global_load_lds_dwordx4 v2, s[0:1]
	s_add_i32 m0, s17, 0x16000
	s_add_i32 s60, s17, 0x4000
	global_load_lds_dwordx4 v136, s[0:1]
	v_readlane_b32 s0, v252, 10
	s_mov_b32 m0, s17
	v_readlane_b32 s1, v252, 11
	s_add_i32 s61, s17, 0x6000
	s_ashr_i32 s35, s9, 8
	s_cmp_eq_u32 s35, 1
	v_mov_b32_e32 v137, v3
	s_cselect_b64 s[36:37], -1, 0
	global_load_lds_dwordx4 v132, s[0:1]
	s_mov_b32 m0, s29
	v_lshl_add_u64 v[6:7], s[84:85], 0, v[2:3]
	global_load_lds_dwordx4 v134, s[0:1]
	v_readlane_b32 s0, v252, 12
	s_mov_b32 m0, s60
	v_readlane_b32 s1, v252, 13
	v_lshl_add_u64 v[4:5], s[84:85], 0, v[136:137]
	s_and_b64 vcc, exec, s[36:37]
	s_nop 2
	global_load_lds_dwordx4 v132, s[0:1]
	s_mov_b32 m0, s61
	s_nop 0
	global_load_lds_dwordx4 v134, s[0:1]
	s_add_u32 s98, s84, 0x80
	s_addc_u32 s99, s85, 0
	s_add_i32 m0, s17, 0x18000
	s_nop 0
	global_load_lds_dwordx4 v2, s[98:99]
	s_add_i32 m0, s17, 0x1a000
	s_nop 0
	global_load_lds_dwordx4 v136, s[98:99]
	v_readlane_b32 s98, v252, 10
	v_readlane_b32 s99, v252, 11
	s_add_u32 s98, s98, 0x80
	s_addc_u32 s99, s99, 0
	s_add_i32 m0, s17, 0x8000
	s_nop 0
	global_load_lds_dwordx4 v132, s[98:99]
	s_add_i32 m0, s17, 0xa000
	s_nop 0
	global_load_lds_dwordx4 v134, s[98:99]
	s_add_u32 s98, s84, 0x80080
	s_addc_u32 s99, s85, 0
	s_add_i32 m0, s17, 0x1c000
	s_nop 0
	global_load_lds_dwordx4 v2, s[98:99]
	s_add_i32 m0, s17, 0x1e000
	s_nop 0
	global_load_lds_dwordx4 v136, s[98:99]
	s_cbranch_vccz .LBB0_513
	s_barrier
.LBB0_513:
	v_readlane_b32 s74, v252, 10
	s_add_u32 s0, s84, 0x80080
	v_mov_b32_e32 v133, v3
	v_readlane_b32 s75, v252, 11
	s_addc_u32 s1, s85, 0
	s_add_i32 m0, s17, 0x18000
	v_lshl_add_u64 v[6:7], v[6:7], 0, s[66:67]
	v_lshl_add_u64 v[16:17], s[74:75], 0, v[132:133]
	v_mov_b32_e32 v135, v3
	s_waitcnt vmcnt(8)
	s_barrier
	v_lshl_add_u64 v[4:5], v[4:5], 0, s[66:67]
	s_add_i32 m0, s17, 0x1a000
	s_add_i32 s62, s17, 0x8000
	v_lshl_add_u64 v[18:19], s[74:75], 0, v[134:135]
	v_lshl_add_u64 v[4:5], v[16:17], 0, s[66:67]
	s_mov_b32 m0, s62
	s_add_i32 s63, s17, 0xa000
	v_lshl_add_u64 v[4:5], v[18:19], 0, s[66:67]
	s_mov_b32 m0, s63
	v_lshrrev_b32_e32 v20, 1, v14
	s_add_i32 m0, s17, 0x1c000
	v_lshl_add_u64 v[4:5], s[0:1], 0, v[2:3]
	v_lshl_add_u64 v[4:5], s[0:1], 0, v[136:137]
	s_add_i32 m0, s17, 0x1e000
	v_and_b32_e32 v20, 24, v20
	v_lshlrev_b32_e32 v4, 15, v8
	v_and_b32_e32 v4, 0xffff0000, v4
	v_lshl_add_u32 v4, v9, 12, v4
	v_and_b32_e32 v5, 1, v8
	v_lshl_or_b32 v4, v5, 6, v4
	s_lshl_b32 s23, s23, 5
	v_lshl_add_u32 v138, v10, 1, v4
	v_lshlrev_b32_e32 v4, 15, v11
	v_and_b32_e32 v15, 15, v14
	v_lshlrev_b32_e32 v21, 1, v20
	v_lshlrev_b32_e32 v14, 2, v14
	s_and_b32 s23, s23, 0x60
	v_and_b32_e32 v4, 0xffff0000, v4
	v_bfe_u32 v1, v0, 2, 4
	v_lshl_or_b32 v1, s35, 6, v1
	v_bfe_u32 v231, v0, 2, 4
	v_and_b32_e32 v230, 3, v0
	v_lshl_or_b32 v231, v230, 4, v231
	v_lshlrev_b32_e32 v231, 2, v231
	v_lshl_or_b32 v15, v15, 6, v21
	v_and_b32_e32 v14, 32, v14
	s_lshl_b32 s35, s35, 13
	s_lshl_b32 s50, s23, 7
	s_waitcnt vmcnt(6)
	v_lshl_add_u32 v4, v12, 12, v4
	v_and_b32_e32 v5, 1, v11
	v_bitop3_b32 v142, v15, s50, v14 bitop3:0xde
	v_bitop3_b32 v14, v15, s35, v14 bitop3:0xde
	s_cmpk_lt_u32 s9, 0x100
	v_lshl_or_b32 v4, v5, 6, v4
	v_readlane_b32 s0, v252, 17
	s_mov_b32 s64, 32
	s_cselect_b64 s[58:59], -1, 0
	v_and_b32_e32 v143, 3, v0
	v_lshl_or_b32 v143, v143, 3, s23
	v_mov_b32_e32 v139, v3
	v_lshl_add_u32 v140, v13, 1, v4
	v_mov_b32_e32 v141, v3
	s_mov_b64 s[86:87], -1
	s_mov_b32 s50, 0
	v_add_u32_e32 v144, 0, v14
	s_mov_b32 s51, s0
	s_barrier
	v_readlane_b32 s1, v252, 18
	s_branch .LBB0_516

.LBB0_685:
	s_or_b64 exec, exec, s[0:1]
	v_readlane_b32 s0, v253, 5
	v_mov_b32_e32 v10, v0
	v_readlane_b32 s1, v253, 6
	s_waitcnt lgkmcnt(0)
	s_barrier
	s_lshl_b32 s9, s49, 24
	s_and_b64 vcc, exec, s[0:1]
	v_readfirstlane_b32 s12, v10
	s_cbranch_vccz .LBB0_701
	v_lshlrev_b32_e32 v1, 4, v10
	v_add_u32_e32 v2, 0x2000, v1
	v_ashrrev_i32_e32 v4, 31, v2
	v_lshrrev_b32_e32 v4, 22, v4
	v_add_u32_e32 v4, v2, v4
	v_ashrrev_i32_e32 v4, 10, v4
	v_mul_i32_i24_e32 v5, 0x400, v4
	v_sub_u32_e32 v2, v2, v5
	v_lshrrev_b32_e32 v5, 4, v2
	v_bitop3_b32 v2, v5, v2, 32 bitop3:0x6c
	v_ashrrev_i32_e32 v5, 31, v2
	v_lshrrev_b32_e32 v5, 26, v5
	v_add_u32_e32 v6, v2, v5
	v_lshlrev_b32_e32 v7, 3, v4
	s_lshl_b32 s0, s9, 1
	v_readlane_b32 s1, v253, 41
	v_ashrrev_i32_e32 v5, 6, v6
	v_and_b32_e32 v7, -16, v7
	s_add_u32 s23, s1, s0
	v_readlane_b32 s0, v253, 42
	v_add_u32_e32 v7, v5, v7
	s_addc_u32 s29, s0, 0
	v_and_b32_e32 v8, 3, v5
	s_mov_b32 s0, 0xfffe0
	v_lshrrev_b32_e32 v9, 2, v7
	v_lshlrev_b32_e32 v11, 1, v7
	v_and_b32_e32 v6, 0xc0, v6
	v_and_or_b32 v8, v7, s0, v8
	v_and_b32_e32 v9, 4, v9
	v_and_b32_e32 v11, 24, v11
	v_sub_u32_e32 v2, v2, v6
	v_or3_b32 v8, v8, v9, v11
	v_lshlrev_b32_e32 v9, 5, v4
	v_ashrrev_i16_sdwa v2, v232, sext(v2) dst_sel:DWORD dst_unused:UNUSED_PAD src0_sel:DWORD src1_sel:BYTE_0
	v_and_b32_e32 v9, 32, v9
	v_bfe_i32 v6, v2, 0, 16
	v_add_lshl_u32 v2, v9, v6, 1
	v_lshl_add_u32 v132, v8, 12, v2
	v_lshl_add_u32 v134, v7, 12, v2
	v_bfe_i32 v2, v10, 27, 1
	v_lshrrev_b32_e32 v2, 22, v2
	v_add_u32_e32 v2, v1, v2
	v_and_b32_e32 v2, 0xfffffc00, v2
	v_sub_u32_e32 v1, v1, v2
	v_lshrrev_b32_e32 v2, 4, v1
	v_ashrrev_i32_e32 v8, 31, v10
	v_bitop3_b32 v1, v2, v1, 32 bitop3:0x6c
	v_lshrrev_b32_e32 v8, 26, v8
	v_ashrrev_i32_e32 v2, 31, v1
	v_add_u32_e32 v8, v10, v8
	v_lshrrev_b32_e32 v2, 26, v2
	v_ashrrev_i32_e32 v8, 6, v8
	v_add_u32_e32 v2, v1, v2
	v_lshlrev_b32_e32 v9, 3, v8
	v_ashrrev_i32_e32 v7, 6, v2
	v_and_b32_e32 v9, -16, v9
	v_add_u32_e32 v11, v7, v9
	v_and_b32_e32 v9, 3, v7
	v_lshrrev_b32_e32 v12, 2, v11
	v_lshlrev_b32_e32 v13, 1, v11
	v_and_b32_e32 v2, 0xc0, v2
	s_ashr_i32 s13, s12, 6
	v_and_or_b32 v9, v11, s0, v9
	v_and_b32_e32 v12, 4, v12
	v_and_b32_e32 v13, 24, v13
	v_sub_u32_e32 v1, v1, v2
	s_ashr_i32 s16, s12, 8
	s_lshl_b32 s35, s13, 10
	v_or3_b32 v12, v9, v12, v13
	v_lshlrev_b32_e32 v9, 5, v8
	v_ashrrev_i16_sdwa v1, v232, sext(v1) dst_sel:DWORD dst_unused:UNUSED_PAD src0_sel:DWORD src1_sel:BYTE_0
	v_readlane_b32 s0, v252, 35
	v_and_b32_e32 v13, 32, v9
	v_bfe_i32 v9, v1, 0, 16
	v_readlane_b32 s1, v252, 36
	s_add_u32 s90, s23, s0
	v_add_lshl_u32 v1, v13, v9, 1
	s_addc_u32 s91, s29, s1
	s_add_i32 s60, s35, 0
	v_lshl_add_u32 v2, v12, 12, v1
	s_add_i32 m0, s60, 0x10000
	v_lshl_add_u32 v136, v11, 12, v1
	global_load_lds_dwordx4 v2, s[90:91]
	s_add_i32 m0, s60, 0x12000
	s_add_u32 s0, s90, 0x80000
	global_load_lds_dwordx4 v132, s[90:91]
	s_addc_u32 s1, s91, 0
	s_add_i32 m0, s60, 0x14000
	s_add_i32 s61, s60, 0x2000
	global_load_lds_dwordx4 v2, s[0:1]
	s_add_i32 m0, s60, 0x16000
	s_add_i32 s62, s60, 0x4000
	global_load_lds_dwordx4 v132, s[0:1]
	v_readlane_b32 s0, v252, 37
	s_mov_b32 m0, s60
	v_readlane_b32 s1, v252, 38
	s_add_i32 s63, s60, 0x6000
	s_cmp_eq_u32 s16, 1
	s_nop 2
	global_load_lds_dwordx4 v136, s[0:1]
	s_mov_b32 m0, s61
	s_nop 0
	global_load_lds_dwordx4 v134, s[0:1]
	v_readlane_b32 s0, v252, 39
	s_mov_b32 m0, s62
	v_readlane_b32 s1, v252, 40
	s_nop 4
	global_load_lds_dwordx4 v136, s[0:1]
	s_mov_b32 m0, s63
	s_nop 0
	global_load_lds_dwordx4 v134, s[0:1]
	s_cselect_b64 s[0:1], -1, 0
	s_add_u32 s98, s90, 0x80
	s_addc_u32 s99, s91, 0
	s_add_i32 m0, s60, 0x18000
	s_nop 0
	global_load_lds_dwordx4 v2, s[98:99]
	s_add_i32 m0, s60, 0x1a000
	s_nop 0
	global_load_lds_dwordx4 v132, s[98:99]
	v_readlane_b32 s98, v252, 37
	v_readlane_b32 s99, v252, 38
	s_add_u32 s98, s98, 0x80
	s_addc_u32 s99, s99, 0
	s_add_i32 m0, s60, 0x8000
	s_nop 0
	global_load_lds_dwordx4 v136, s[98:99]
	s_add_i32 m0, s60, 0xa000
	s_nop 0
	global_load_lds_dwordx4 v134, s[98:99]
	s_add_u32 s98, s90, 0x80080
	s_addc_u32 s99, s91, 0
	s_add_i32 m0, s60, 0x1c000
	s_nop 0
	global_load_lds_dwordx4 v2, s[98:99]
	s_add_i32 m0, s60, 0x1e000
	s_nop 0
	global_load_lds_dwordx4 v132, s[98:99]
	s_cmp_lg_u32 s16, 1
	s_cbranch_scc1 .LBB0_688
	s_barrier
.LBB0_688:
	v_lshrrev_b32_e32 v20, 1, v10
	v_and_b32_e32 v20, 24, v20
	v_and_b32_e32 v11, 15, v10
	v_lshlrev_b32_e32 v21, 1, v20
	v_lshlrev_b32_e32 v10, 2, v10
	s_lshl_b32 s13, s13, 5
	v_bfe_u32 v1, v0, 2, 4
	v_lshl_or_b32 v1, s16, 6, v1
	v_bfe_u32 v231, v0, 2, 4
	v_and_b32_e32 v230, 3, v0
	v_lshl_or_b32 v231, v230, 4, v231
	v_lshlrev_b32_e32 v231, 2, v231
	v_lshl_or_b32 v11, v11, 6, v21
	s_lshl_b32 s16, s16, 13
	v_and_b32_e32 v10, 32, v10
	s_and_b32 s13, s13, 0x60
	v_lshl_add_u64 v[12:13], s[90:91], 0, v[2:3]
	v_mov_b32_e32 v133, v3
	v_readlane_b32 s88, v252, 37
	v_bitop3_b32 v21, v11, s16, v10 bitop3:0xde
	s_lshl_b32 s16, s13, 7
	v_lshl_add_u64 v[14:15], s[90:91], 0, v[132:133]
	v_mov_b32_e32 v137, v3
	v_readlane_b32 s89, v252, 38
	v_bitop3_b32 v144, v11, s16, v10 bitop3:0xde
	s_add_i32 m0, s60, 0x18000
	v_lshl_add_u64 v[10:11], v[12:13], 0, s[66:67]
	v_lshl_add_u64 v[16:17], s[88:89], 0, v[136:137]
	v_mov_b32_e32 v135, v3
	s_waitcnt vmcnt(8)
	s_barrier
	v_lshl_add_u64 v[10:11], v[14:15], 0, s[66:67]
	s_add_i32 m0, s60, 0x1a000
	s_add_i32 s64, s60, 0x8000
	s_add_i32 s58, s60, 0xa000
	v_lshl_add_u64 v[18:19], s[88:89], 0, v[134:135]
	v_lshl_add_u64 v[10:11], v[16:17], 0, s[66:67]
	s_mov_b32 m0, s64
	s_add_u32 s16, s90, 0x80080
	v_lshl_add_u64 v[10:11], v[18:19], 0, s[66:67]
	s_mov_b32 m0, s58
	s_addc_u32 s17, s91, 0
	s_add_i32 m0, s60, 0x1c000
	v_lshl_add_u64 v[10:11], s[16:17], 0, v[2:3]
	v_lshl_add_u64 v[10:11], s[16:17], 0, v[132:133]
	s_add_i32 m0, s60, 0x1e000
	s_cmpk_lt_u32 s12, 0x100
	v_lshlrev_b32_e32 v10, 15, v8
	v_and_b32_e32 v10, 0xffff0000, v10
	v_lshl_add_u32 v7, v7, 12, v10
	v_and_b32_e32 v8, 1, v8
	v_lshl_or_b32 v7, v8, 6, v7
	v_lshl_add_u32 v138, v9, 1, v7
	v_lshlrev_b32_e32 v7, 15, v4
	v_and_b32_e32 v7, 0xffff0000, v7
	s_waitcnt vmcnt(6)
	v_lshl_add_u32 v5, v5, 12, v7
	v_and_b32_e32 v4, 1, v4
	v_lshl_or_b32 v4, v4, 6, v5
	v_readlane_b32 s16, v252, 33
	s_cselect_b64 s[68:69], -1, 0
	v_and_b32_e32 v145, 3, v0
	v_lshl_or_b32 v145, v145, 3, s13
	v_mov_b32_e32 v139, v3
	v_lshl_add_u32 v140, v6, 1, v4
	v_mov_b32_e32 v141, v3
	s_mov_b32 s59, 0
	v_add_u32_e32 v146, 0, v21
	v_readlane_b32 s12, v252, 32
	s_mov_b32 s13, s16
	s_barrier
	v_readlane_b32 s17, v252, 34
	s_branch .LBB0_691

.LBB0_753:
	s_or_b64 exec, exec, s[0:1]
	v_mov_b32_e32 v14, v0
	s_waitcnt lgkmcnt(0)
	s_barrier
	s_lshl_b32 s0, s9, 1
	v_ashrrev_i32_e32 v2, 31, v14
	v_lshrrev_b32_e32 v2, 26, v2
	v_add_u32_e32 v2, v14, v2
	v_ashrrev_i32_e32 v8, 6, v2
	v_bfe_i32 v2, v14, 27, 1
	v_lshlrev_b32_e32 v1, 4, v14
	v_lshrrev_b32_e32 v2, 22, v2
	v_add_u32_e32 v2, v1, v2
	v_and_b32_e32 v2, 0xfffffc00, v2
	v_sub_u32_e32 v2, v1, v2
	v_lshrrev_b32_e32 v4, 4, v2
	v_bitop3_b32 v2, v4, v2, 32 bitop3:0x6c
	v_ashrrev_i32_e32 v5, 31, v2
	v_lshrrev_b32_e32 v5, 26, v5
	v_add_u32_e32 v5, v2, v5
	v_lshlrev_b32_e32 v4, 3, v8
	v_ashrrev_i32_e32 v9, 6, v5
	v_and_b32_e32 v5, 0xc0, v5
	v_and_b32_e32 v4, -16, v4
	v_sub_u32_e32 v2, v2, v5
	v_readlane_b32 s1, v253, 39
	v_add_u32_e32 v4, v9, v4
	v_ashrrev_i16_sdwa v2, v232, sext(v2) dst_sel:DWORD dst_unused:UNUSED_PAD src0_sel:DWORD src1_sel:BYTE_0
	s_add_u32 s9, s1, s0
	v_lshlrev_b32_e32 v6, 5, v8
	v_bfe_i32 v10, v2, 0, 16
	v_lshlrev_b32_e32 v2, 1, v4
	v_lshrrev_b32_e32 v5, 2, v4
	v_and_b32_e32 v7, 3, v9
	s_mov_b32 s1, 0x3ffe0
	v_and_b32_e32 v6, 32, v6
	v_and_b32_e32 v2, 24, v2
	v_and_b32_e32 v5, 4, v5
	v_and_or_b32 v7, v4, s1, v7
	v_or3_b32 v2, v7, v5, v2
	v_add_lshl_u32 v5, v6, v10, 1
	v_add_u32_e32 v1, 0x2000, v1
	v_lshl_add_u32 v132, v4, 14, v5
	v_ashrrev_i32_e32 v4, 31, v1
	v_lshrrev_b32_e32 v4, 22, v4
	v_add_u32_e32 v4, v1, v4
	v_ashrrev_i32_e32 v11, 10, v4
	v_mul_i32_i24_e32 v4, 0x400, v11
	v_sub_u32_e32 v1, v1, v4
	v_lshrrev_b32_e32 v4, 4, v1
	v_bitop3_b32 v1, v4, v1, 32 bitop3:0x6c
	v_readlane_b32 s0, v253, 40
	v_lshl_add_u32 v2, v2, 14, v5
	v_ashrrev_i32_e32 v5, 31, v1
	s_addc_u32 s12, s0, 0
	v_readlane_b32 s0, v252, 19
	v_lshrrev_b32_e32 v5, 26, v5
	s_add_u32 s86, s9, s0
	v_lshlrev_b32_e32 v4, 3, v11
	v_add_u32_e32 v5, v1, v5
	s_addc_u32 s87, s12, 0
	v_and_b32_e32 v4, -16, v4
	v_ashrrev_i32_e32 v12, 6, v5
	v_and_b32_e32 v5, 0xc0, v5
	s_add_u32 s36, s86, 0x200000
	v_readfirstlane_b32 s0, v14
	v_add_u32_e32 v4, v12, v4
	v_sub_u32_e32 v1, v1, v5
	v_and_b32_e32 v7, 3, v12
	s_addc_u32 s37, s87, 0
	v_ashrrev_i16_sdwa v1, v232, sext(v1) dst_sel:DWORD dst_unused:UNUSED_PAD src0_sel:DWORD src1_sel:BYTE_0
	v_and_or_b32 v7, v4, s1, v7
	s_ashr_i32 s1, s0, 6
	v_lshlrev_b32_e32 v6, 5, v11
	v_bfe_i32 v13, v1, 0, 16
	v_lshlrev_b32_e32 v1, 1, v4
	v_lshrrev_b32_e32 v5, 2, v4
	s_lshl_b32 s13, s1, 10
	v_and_b32_e32 v6, 32, v6
	v_and_b32_e32 v1, 24, v1
	v_and_b32_e32 v5, 4, v5
	s_add_i32 s16, s13, 0
	v_or3_b32 v1, v7, v5, v1
	v_add_lshl_u32 v5, v6, v13, 1
	s_add_i32 m0, s16, 0x10000
	v_lshl_add_u32 v136, v1, 14, v5
	global_load_lds_dwordx4 v2, s[86:87]
	s_add_i32 m0, s16, 0x12000
	s_add_i32 s17, s16, 0x2000
	global_load_lds_dwordx4 v136, s[86:87]
	s_add_i32 m0, s16, 0x14000
	v_lshl_add_u32 v134, v4, 14, v5
	global_load_lds_dwordx4 v2, s[36:37]
	s_add_i32 m0, s16, 0x16000
	s_add_i32 s58, s16, 0x4000
	global_load_lds_dwordx4 v136, s[36:37]
	v_readlane_b32 s36, v252, 20
	s_mov_b32 m0, s16
	v_readlane_b32 s37, v252, 21
	s_add_i32 s59, s16, 0x6000
	s_ashr_i32 s23, s0, 8
	v_mov_b32_e32 v137, v3
	s_cmp_eq_u32 s23, 1
	v_lshl_add_u64 v[4:5], s[86:87], 0, v[2:3]
	global_load_lds_dwordx4 v132, s[36:37]
	s_mov_b32 m0, s17
	v_lshl_add_u64 v[6:7], s[86:87], 0, v[136:137]
	global_load_lds_dwordx4 v134, s[36:37]
	v_readlane_b32 s36, v252, 22
	s_mov_b32 m0, s58
	v_readlane_b32 s37, v252, 23
	s_nop 4
	global_load_lds_dwordx4 v132, s[36:37]
	s_mov_b32 m0, s59
	s_nop 0
	global_load_lds_dwordx4 v134, s[36:37]
	s_cselect_b64 s[36:37], -1, 0
	s_add_u32 s98, s86, 0x80
	s_addc_u32 s99, s87, 0
	s_add_i32 m0, s16, 0x18000
	s_nop 0
	global_load_lds_dwordx4 v2, s[98:99]
	s_add_i32 m0, s16, 0x1a000
	s_nop 0
	global_load_lds_dwordx4 v136, s[98:99]
	v_readlane_b32 s98, v252, 20
	v_readlane_b32 s99, v252, 21
	s_add_u32 s98, s98, 0x80
	s_addc_u32 s99, s99, 0
	s_add_i32 m0, s16, 0x8000
	s_nop 0
	global_load_lds_dwordx4 v132, s[98:99]
	s_add_i32 m0, s16, 0xa000
	s_nop 0
	global_load_lds_dwordx4 v134, s[98:99]
	s_add_u32 s98, s86, 0x200080
	s_addc_u32 s99, s87, 0
	s_add_i32 m0, s16, 0x1c000
	s_nop 0
	global_load_lds_dwordx4 v2, s[98:99]
	s_add_i32 m0, s16, 0x1e000
	s_nop 0
	global_load_lds_dwordx4 v136, s[98:99]
	s_cmp_lg_u32 s23, 1
	s_cbranch_scc1 .LBB0_755
	s_barrier
.LBB0_755:
	v_readlane_b32 s84, v252, 20
	s_add_u32 s50, s86, 0x200080
	v_mov_b32_e32 v133, v3
	v_readlane_b32 s85, v252, 21
	s_addc_u32 s51, s87, 0
	s_add_i32 m0, s16, 0x18000
	v_lshl_add_u64 v[4:5], v[4:5], 0, s[66:67]
	v_lshl_add_u64 v[16:17], s[84:85], 0, v[132:133]
	v_mov_b32_e32 v135, v3
	s_waitcnt vmcnt(8)
	s_barrier
	v_lshl_add_u64 v[4:5], v[6:7], 0, s[66:67]
	s_add_i32 m0, s16, 0x1a000
	s_add_i32 s60, s16, 0x8000
	v_lshl_add_u64 v[18:19], s[84:85], 0, v[134:135]
	v_lshl_add_u64 v[4:5], v[16:17], 0, s[66:67]
	s_mov_b32 m0, s60
	s_add_i32 s61, s16, 0xa000
	v_lshl_add_u64 v[4:5], v[18:19], 0, s[66:67]
	s_mov_b32 m0, s61
	v_lshrrev_b32_e32 v20, 1, v14
	s_add_i32 m0, s16, 0x1c000
	v_lshl_add_u64 v[4:5], s[50:51], 0, v[2:3]
	v_lshl_add_u64 v[4:5], s[50:51], 0, v[136:137]
	s_add_i32 m0, s16, 0x1e000
	v_and_b32_e32 v20, 24, v20
	v_lshlrev_b32_e32 v4, 17, v8
	v_and_b32_e32 v4, 0xfffc0000, v4
	v_lshl_add_u32 v4, v9, 14, v4
	v_and_b32_e32 v5, 1, v8
	v_lshl_or_b32 v4, v5, 6, v4
	s_lshl_b32 s1, s1, 5
	v_lshl_add_u32 v138, v10, 1, v4
	v_lshlrev_b32_e32 v4, 17, v11
	v_and_b32_e32 v15, 15, v14
	v_lshlrev_b32_e32 v21, 1, v20
	v_lshlrev_b32_e32 v14, 2, v14
	s_and_b32 s1, s1, 0x60
	v_and_b32_e32 v4, 0xfffc0000, v4
	v_bfe_u32 v1, v0, 2, 4
	v_lshl_or_b32 v1, s23, 6, v1
	v_bfe_u32 v231, v0, 2, 4
	v_and_b32_e32 v230, 3, v0
	v_lshl_or_b32 v231, v230, 4, v231
	v_lshlrev_b32_e32 v231, 2, v231
	v_lshl_or_b32 v15, v15, 6, v21
	v_and_b32_e32 v14, 32, v14
	s_lshl_b32 s23, s23, 13
	s_lshl_b32 s29, s1, 7
	s_waitcnt vmcnt(6)
	v_lshl_add_u32 v4, v12, 14, v4
	v_and_b32_e32 v5, 1, v11
	v_bitop3_b32 v142, v15, s29, v14 bitop3:0xde
	v_bitop3_b32 v14, v15, s23, v14 bitop3:0xde
	s_cmpk_lt_u32 s0, 0x100
	v_and_b32_e32 v143, 3, v0
	v_lshl_or_b32 v143, v143, 3, s1
	v_lshl_or_b32 v4, v5, 6, v4
	v_readlane_b32 s0, v252, 17
	s_cselect_b64 s[68:69], -1, 0
	v_mov_b32_e32 v139, v3
	v_lshl_add_u32 v140, v13, 1, v4
	v_mov_b32_e32 v141, v3
	s_mov_b64 s[88:89], -1
	s_movk_i32 s51, 0x80
	s_mov_b32 s50, 0
	v_add_u32_e32 v144, 0, v14
	s_mov_b32 s54, s0
	s_barrier
	v_readlane_b32 s1, v252, 18
	s_branch .LBB0_758
